# v15 + P10 token top: next token's expert ids/weights requested one token ahead, ring fill issued before the x row is waited for
# speedup vs baseline: 1.0000x; 1.0000x over previous
; __device__ __forceinline__ void peer_gather(const Frame& F, int l) {
;     const Args A = load_args();
;     int lane = F.lane; asm volatile("" : "+v"(lane));
;     __attribute__((address_space(1))) unsigned char* wsl_ = (__attribute__((address_space(1))) unsigned char*)F.ws; asm volatile("" : "+s"(wsl_)); unsigned char* ws = (unsigned char*)wsl_;
;     const unsigned char* Ub = ws + WS_U + (size_t)l * NEXP * 1024; const unsigned char* Ue = ws + WS_ESC + (size_t)l * NEXP * 128;
;     const unsigned char* Vb = ws + WS_V + (size_t)l * NEXP * 1024; const unsigned char* Ve = Ue + 64;
;     bf16_t* XBp = (bf16_t*)(ws + WS_XB);
;     const float* g2 = A.in[I_LN2G] + l * D; const float* b2 = A.in[I_LN2B] + l * D;
;     for (int t = F.bid * NWAVES + F.wave; t < M; t += F.G * NWAVES) {
.LBB0_2085:
	s_or_b64 exec, exec, s[0:1]
	v_readlane_b32 s0, v254, 1
	v_readlane_b32 s7, v254, 0
	v_readlane_b32 s8, v254, 9
	v_readlane_b32 s1, v254, 2
	v_readlane_b32 s6, v254, 3
	s_waitcnt lgkmcnt(0)
	s_barrier
	s_lshl_b32 s7, s7, 3
	s_add_i32 s8, s7, s8
	v_mbcnt_lo_u32_b32 v92, -1, 0
	v_mbcnt_hi_u32_b32 v92, -1, v92
	v_readlane_b32 s26, v254, 21
	s_mov_b64 s[4:5], s[96:97]
	s_cmpk_gt_i32 s8, 0x27ff
	v_readlane_b32 s27, v254, 22
	s_cbranch_scc1 .LBB0_2248
	s_ashr_i32 s27, s26, 31
	s_load_dwordx4 s[20:23], s[4:5], 0xf8
	s_load_dwordx2 s[10:11], s[4:5], 0x108
	s_lshl_b64 s[4:5], s[26:27], 24
	s_add_u32 s7, s0, s4
	s_addc_u32 s9, s1, s5
	s_add_u32 s12, s7, 0xbe40000
	s_addc_u32 s13, s9, 0
	s_lshl_b64 s[4:5], s[26:27], 21
	s_add_u32 s4, s0, s4
	s_addc_u32 s5, s1, s5
	s_add_u32 s14, s4, 0xde40000
	s_addc_u32 s15, s5, 0
	s_add_u32 s16, s7, 0x13e40000
	s_addc_u32 s17, s9, 0
	s_add_u32 s33, s0, 0x1be40000
	s_addc_u32 s34, s1, 0
	s_lshl_b32 s4, s26, 11
	s_ashr_i32 s5, s4, 31
	s_lshl_b64 s[4:5], s[4:5], 2
	s_waitcnt lgkmcnt(0)
	s_add_u32 s18, s20, s4
	s_addc_u32 s19, s21, s5
	s_add_u32 s20, s22, s4
	s_addc_u32 s21, s23, s5
	s_add_u32 s22, s0, 0x4a0d0000
	s_addc_u32 s23, s1, 0
	s_add_u32 s24, s0, 0x4a5d0000
	s_addc_u32 s25, s1, 0
	s_cmp_lg_u32 s26, 1
	s_cselect_b64 s[26:27], -1, 0
	s_add_u32 s35, s0, 0x11e40000
	s_addc_u32 s36, s1, 0
	s_lshl_b32 s37, s6, 3
	s_mov_b32 s99, 0
	s_branch .LBB0_2088

; __device__ __forceinline__ float bflo(unsigned w) { return __uint_as_float(w << 16); }
; __device__ __forceinline__ float bfhi(unsigned w) { return __uint_as_float(w & 0xffff0000u); }
; __device__ __forceinline__ void peer_gather(const Frame& F, int l) {
;     ...
;     for (int t = F.bid * NWAVES + F.wave; t < M; t += F.G * NWAVES) {
;         asm volatile("" : "+v"(lane));
;         int e0 = ((const int*)(ws + WS_EID))[(size_t)t * 128 + lane], e1 = ((const int*)(ws + WS_EID))[(size_t)t * 128 + 64 + lane];
;         const float w0 = ((const float*)(ws + WS_GW))[(size_t)t * 128 + lane], w1 = ((const float*)(ws + WS_GW))[(size_t)t * 128 + 64 + lane];
;         u32x4 xw4[4];
; #pragma unroll
;         for (int q = 0; q < 4; ++q) xw4[q] = *(const u32x4*)(XBp + (size_t)t * D + 32 * lane + 8 * q);
;         asm volatile("" : "+v"(e0), "+v"(e1));
;         f32x2 xp[16];
;         f32x2 acc[16];
; #pragma unroll
;         for (int j = 0; j < 16; ++j) acc[j] = (f32x2){0.f, 0.f};
;         u32x4 rr[16]; float rsc[16];
;     ...
; #pragma unroll
;         for (int s = 0; s < 15; ++s) PG_STEP(s, 0);
; #pragma unroll
;         for (int q = 0; q < 4; ++q) { const u32x4 w = xw4[q];
;             xp[4 * q] = (f32x2){bflo(w.x), bfhi(w.x)}; xp[4 * q + 1] = (f32x2){bflo(w.y), bfhi(w.y)}; xp[4 * q + 2] = (f32x2){bflo(w.z), bfhi(w.z)}; xp[4 * q + 3] = (f32x2){bflo(w.w), bfhi(w.w)}; }
.LBB0_2088:
	s_ashr_i32 s9, s8, 31
	s_lshl_b64 s[28:29], s[8:9], 12
	v_ashrrev_i32_e32 v93, 31, v92
	v_lshlrev_b32_e32 v94, 5, v92
	v_ashrrev_i32_e32 v95, 31, v94
	s_cmp_eq_u32 s99, 0
	s_cbranch_scc0 .Lp10_have_ew
	s_lshl_b64 s[0:1], s[8:9], 7
	v_lshl_add_u64 v[190:191], s[0:1], 0, v[92:93]
	v_lshlrev_b64 v[190:191], 2, v[190:191]
	v_lshl_add_u64 v[0:1], s[22:23], 0, v[190:191]
	global_load_dword v198, v[0:1], off
	global_load_dword v199, v[0:1], off offset:256
	v_lshl_add_u64 v[0:1], s[24:25], 0, v[190:191]
	global_load_dword v200, v[0:1], off
	global_load_dword v166, v[0:1], off offset:256
	s_mov_b32 s99, 1
.Lp10_have_ew:
	s_add_u32 s0, s33, s28
	s_addc_u32 s1, s34, s29
	v_lshl_add_u64 v[0:1], v[94:95], 1, s[0:1]
	global_load_dwordx4 v[150:153], v[0:1], off offset:48
	global_load_dwordx4 v[154:157], v[0:1], off offset:32
	global_load_dwordx4 v[158:161], v[0:1], off offset:16
	global_load_dwordx4 v[162:165], v[0:1], off
	s_waitcnt vmcnt(4)
	v_mov_b32_e32 v167, v198
	v_mov_b32_e32 v168, v199
	v_mov_b32_e32 v169, v200
	v_mov_b32_e32 v170, v166
	s_add_i32 s0, s8, s37
	s_cmpk_lt_i32 s0, 0x2800
	s_cselect_b32 s0, s0, s8
	s_ashr_i32 s1, s0, 31
	s_lshl_b64 s[0:1], s[0:1], 7
	v_lshl_add_u64 v[190:191], s[0:1], 0, v[92:93]
	v_lshlrev_b64 v[190:191], 2, v[190:191]
	v_lshl_add_u64 v[0:1], s[22:23], 0, v[190:191]
	global_load_dword v198, v[0:1], off
	global_load_dword v199, v[0:1], off offset:256
	v_lshl_add_u64 v[0:1], s[24:25], 0, v[190:191]
	global_load_dword v200, v[0:1], off
	global_load_dword v166, v[0:1], off offset:256
	v_lshlrev_b32_e32 v196, 4, v92
	v_add_u32_e32 v194, 8, v92
	v_and_b32_e32 v194, 63, v194
	v_lshlrev_b32_e32 v194, 2, v194
	v_xor_b32_e32 v197, 16, v92
	v_lshlrev_b32_e32 v197, 2, v197
	v_xor_b32_e32 v89, 32, v92
	v_lshlrev_b32_e32 v89, 2, v89
	v_xor_b32_e32 v90, 48, v92
	v_lshlrev_b32_e32 v90, 2, v90
	ds_bpermute_b32 v192, v194, v167
	v_mov_b32_e32 v193, v169
	s_mov_b32 vcc_lo, 0xaaaaaaaa
	s_mov_b32 vcc_hi, 0xaaaaaaaa
	s_mov_b32 s100, 0xcccccccc
	s_mov_b32 s101, 0xcccccccc
	v_readlane_b32 s0, v167, 0
	v_readlane_b32 s1, v167, 1
	v_readlane_b32 s4, v167, 2
	v_readlane_b32 s5, v167, 3
	v_readlane_b32 s6, v167, 4
	v_readlane_b32 s7, v167, 5
	v_readlane_b32 s58, v167, 6
	v_readlane_b32 s59, v167, 7
	s_nop 1
	v_lshl_add_u32 v87, s0, 10, v196
	v_lshl_add_u32 v88, s0, 7, v92
	global_load_dwordx4 v[0:3], v87, s[12:13]
	global_load_ubyte v64, v88, s[14:15]
	v_lshl_add_u32 v87, s1, 10, v196
	v_lshl_add_u32 v88, s1, 7, v92
	global_load_dwordx4 v[4:7], v87, s[12:13]
	global_load_ubyte v65, v88, s[14:15]
	v_lshl_add_u32 v87, s4, 10, v196
	v_lshl_add_u32 v88, s4, 7, v92
	global_load_dwordx4 v[8:11], v87, s[12:13]
	global_load_ubyte v66, v88, s[14:15]
	v_lshl_add_u32 v87, s5, 10, v196
	v_lshl_add_u32 v88, s5, 7, v92
	global_load_dwordx4 v[12:15], v87, s[12:13]
	global_load_ubyte v67, v88, s[14:15]
	v_lshl_add_u32 v87, s6, 10, v196
	v_lshl_add_u32 v88, s6, 7, v92
	global_load_dwordx4 v[16:19], v87, s[12:13]
	global_load_ubyte v68, v88, s[14:15]
	v_lshl_add_u32 v87, s7, 10, v196
	v_lshl_add_u32 v88, s7, 7, v92
	global_load_dwordx4 v[20:23], v87, s[12:13]
	global_load_ubyte v69, v88, s[14:15]
	v_lshl_add_u32 v87, s58, 10, v196
	v_lshl_add_u32 v88, s58, 7, v92
	global_load_dwordx4 v[24:27], v87, s[12:13]
	global_load_ubyte v70, v88, s[14:15]
	v_lshl_add_u32 v87, s59, 10, v196
	v_lshl_add_u32 v88, s59, 7, v92
	global_load_dwordx4 v[28:31], v87, s[12:13]
	global_load_ubyte v71, v88, s[14:15]
	v_lshl_add_u32 v87, s0, 10, v196
	v_lshl_add_u32 v88, s0, 7, v92
	global_load_dwordx4 v[32:35], v87, s[16:17]
	global_load_ubyte v72, v88, s[14:15] offset:64
	v_lshl_add_u32 v87, s1, 10, v196
	v_lshl_add_u32 v88, s1, 7, v92
	global_load_dwordx4 v[36:39], v87, s[16:17]
	global_load_ubyte v73, v88, s[14:15] offset:64
	v_lshl_add_u32 v87, s4, 10, v196
	v_lshl_add_u32 v88, s4, 7, v92
	global_load_dwordx4 v[40:43], v87, s[16:17]
	global_load_ubyte v74, v88, s[14:15] offset:64
	v_lshl_add_u32 v87, s5, 10, v196
	v_lshl_add_u32 v88, s5, 7, v92
	global_load_dwordx4 v[44:47], v87, s[16:17]
	global_load_ubyte v75, v88, s[14:15] offset:64
	v_lshl_add_u32 v87, s6, 10, v196
	v_lshl_add_u32 v88, s6, 7, v92
	global_load_dwordx4 v[48:51], v87, s[16:17]
	global_load_ubyte v76, v88, s[14:15] offset:64
	v_lshl_add_u32 v87, s7, 10, v196
	v_lshl_add_u32 v88, s7, 7, v92
	global_load_dwordx4 v[52:55], v87, s[16:17]
	global_load_ubyte v77, v88, s[14:15] offset:64
	v_lshl_add_u32 v87, s58, 10, v196
	v_lshl_add_u32 v88, s58, 7, v92
	global_load_dwordx4 v[56:59], v87, s[16:17]
	global_load_ubyte v78, v88, s[14:15] offset:64
	v_lshl_add_u32 v87, s59, 10, v196
	v_lshl_add_u32 v88, s59, 7, v92
	global_load_dwordx4 v[60:63], v87, s[16:17]
	global_load_ubyte v79, v88, s[14:15] offset:64
	s_waitcnt vmcnt(36)
	v_lshlrev_b32_e32 v132, 16, v162
	v_and_b32_e32 v133, 0xffff0000, v162
	v_lshlrev_b32_e32 v130, 16, v163
	v_and_b32_e32 v131, 0xffff0000, v163
	v_lshlrev_b32_e32 v128, 16, v164
	v_and_b32_e32 v129, 0xffff0000, v164
	v_lshlrev_b32_e32 v126, 16, v165
	v_and_b32_e32 v127, 0xffff0000, v165
	v_lshlrev_b32_e32 v124, 16, v158
	v_and_b32_e32 v125, 0xffff0000, v158
	v_lshlrev_b32_e32 v122, 16, v159
	v_and_b32_e32 v123, 0xffff0000, v159
	v_lshlrev_b32_e32 v120, 16, v160
	v_and_b32_e32 v121, 0xffff0000, v160
	v_lshlrev_b32_e32 v118, 16, v161
	v_and_b32_e32 v119, 0xffff0000, v161
	v_lshlrev_b32_e32 v116, 16, v154
	v_and_b32_e32 v117, 0xffff0000, v154
	v_lshlrev_b32_e32 v114, 16, v155
	v_and_b32_e32 v115, 0xffff0000, v155
	v_lshlrev_b32_e32 v112, 16, v156
	v_and_b32_e32 v113, 0xffff0000, v156
	v_lshlrev_b32_e32 v110, 16, v157
	v_and_b32_e32 v111, 0xffff0000, v157
	v_lshlrev_b32_e32 v106, 16, v150
	v_and_b32_e32 v107, 0xffff0000, v150
	v_lshlrev_b32_e32 v108, 16, v151
	v_and_b32_e32 v109, 0xffff0000, v151
	v_lshlrev_b32_e32 v104, 16, v152
	v_and_b32_e32 v105, 0xffff0000, v152
	v_lshlrev_b32_e32 v102, 16, v153
	v_and_b32_e32 v103, 0xffff0000, v153
	v_mov_b32_e32 v164, 0
	v_mov_b32_e32 v165, 0
	v_mov_b32_e32 v162, 0
	v_mov_b32_e32 v163, 0
	v_mov_b32_e32 v160, 0
	v_mov_b32_e32 v161, 0
	v_mov_b32_e32 v158, 0
	v_mov_b32_e32 v159, 0
	v_mov_b32_e32 v156, 0
	v_mov_b32_e32 v157, 0
	v_mov_b32_e32 v154, 0
	v_mov_b32_e32 v155, 0
	v_mov_b32_e32 v152, 0
	v_mov_b32_e32 v153, 0
	v_mov_b32_e32 v150, 0
	v_mov_b32_e32 v151, 0
	v_mov_b32_e32 v148, 0
	v_mov_b32_e32 v149, 0
	v_mov_b32_e32 v146, 0
	v_mov_b32_e32 v147, 0
	v_mov_b32_e32 v144, 0
	v_mov_b32_e32 v145, 0
	v_mov_b32_e32 v142, 0
	v_mov_b32_e32 v143, 0
	v_mov_b32_e32 v140, 0
	v_mov_b32_e32 v141, 0
	v_mov_b32_e32 v138, 0
	v_mov_b32_e32 v139, 0
	v_mov_b32_e32 v136, 0
	v_mov_b32_e32 v137, 0
	v_mov_b32_e32 v134, 0
	v_mov_b32_e32 v135, 0
	s_mov_b32 s30, 0
	s_waitcnt lgkmcnt(0)
